# mixer to mixer-out barrier: workgroups that are not their XCD's last arriver wait for the release inside the mixer-out GEMM preamble, after its weight-tile loads have issued
# speedup vs baseline: 1.0023x; 1.0019x over previous
.LBB0_939:
	s_or_b64 exec, exec, s[12:13]
	v_cvt_f32_u32_e32 v4, v2
	s_waitcnt vmcnt(0)
	v_readfirstlane_b32 s2, v3
	v_sub_u32_e32 v3, 0, v2
	v_rcp_iflag_f32_e32 v4, v4
	v_add_u32_e32 v5, s2, v1
	v_mul_f32_e32 v4, 0x4f7ffffe, v4
	v_cvt_u32_f32_e32 v4, v4
	v_mul_lo_u32 v1, v3, v4
	v_mul_hi_u32 v1, v4, v1
	v_add_u32_e32 v1, v4, v1
	v_mul_hi_u32 v1, v5, v1
	v_mul_lo_u32 v3, v1, v2
	v_sub_u32_e32 v3, v5, v3
	v_add_u32_e32 v4, 1, v1
	v_cmp_ge_u32_e32 vcc, v3, v2
	s_nop 1
	v_cndmask_b32_e32 v1, v1, v4, vcc
	v_sub_u32_e32 v4, v3, v2
	v_cndmask_b32_e32 v3, v3, v4, vcc
	v_add_u32_e32 v4, 1, v1
	v_cmp_ge_u32_e32 vcc, v3, v2
	v_add_u32_e32 v3, 1, v5
	s_nop 0
	v_cndmask_b32_e32 v1, v1, v4, vcc
	v_mul_lo_u32 v4, v2, v1
	v_add_u32_e32 v2, v4, v2
	v_cmp_ne_u32_e32 vcc, v3, v2
	s_and_saveexec_b64 s[10:11], vcc
	s_xor_b64 s[10:11], exec, s[10:11]
	s_cbranch_execz .LBB0_953
	v_readlane_b32 s18, v255, 0
	s_nop 0
	s_cmp_lt_u32 s18, 0x80
	s_cbranch_scc0 .Lb5_std
	s_bitcmp0_b32 s18, 0
	s_cbranch_scc0 .Lb5_std
	s_bfe_u32 s19, s18, 0x30003
	s_bfe_u32 s18, s18, 0x20001
	s_lshl_b32 s18, s18, 3
	s_or_b32 s18, s18, s19
	s_lshl_b32 s18, s18, 7
	s_add_u32 s18, s18, 0xb000
	v_readlane_b32 s19, v255, 47
	s_mov_b32 s2, 0
	s_waitcnt lgkmcnt(0)
	v_mov_b32_e32 v0, s18

.LBB0_1111:
	s_or_b64 exec, exec, s[14:15]
	v_cvt_f32_u32_e32 v4, v2
	s_waitcnt vmcnt(0)
	v_readfirstlane_b32 s2, v3
	v_sub_u32_e32 v3, 0, v2
	v_rcp_iflag_f32_e32 v4, v4
	v_add_u32_e32 v5, s2, v1
	v_mul_f32_e32 v4, 0x4f7ffffe, v4
	v_cvt_u32_f32_e32 v4, v4
	v_mul_lo_u32 v1, v3, v4
	v_mul_hi_u32 v1, v4, v1
	v_add_u32_e32 v1, v4, v1
	v_mul_hi_u32 v1, v5, v1
	v_mul_lo_u32 v3, v1, v2
	v_sub_u32_e32 v3, v5, v3
	v_add_u32_e32 v4, 1, v1
	v_cmp_ge_u32_e32 vcc, v3, v2
	s_nop 1
	v_cndmask_b32_e32 v1, v1, v4, vcc
	v_sub_u32_e32 v4, v3, v2
	v_cndmask_b32_e32 v3, v3, v4, vcc
	v_add_u32_e32 v4, 1, v1
	v_cmp_ge_u32_e32 vcc, v3, v2
	v_add_u32_e32 v3, 1, v5
	s_nop 0
	v_cndmask_b32_e32 v1, v1, v4, vcc
	v_mul_lo_u32 v4, v2, v1
	v_add_u32_e32 v2, v4, v2
	v_cmp_ne_u32_e32 vcc, v3, v2
	s_and_saveexec_b64 s[12:13], vcc
	s_xor_b64 s[12:13], exec, s[12:13]
	s_cbranch_execz .LBB0_1125
	s_waitcnt lgkmcnt(0)
	s_sub_u32 s18, s10, s6
	s_add_u32 s18, s18, 0x2400
	v_readfirstlane_b32 s19, v1
	s_nop 0
	s_add_u32 s19, s19, 1
	v_writelane_b32 v255, s18, 50
	v_writelane_b32 v255, s19, 51
	v_writelane_b32 v255, s18, 52
	v_writelane_b32 v255, s19, 53
	v_writelane_b32 v255, s6, 54
	v_writelane_b32 v255, s7, 55
	s_branch .Lb6_join
	global_load_dword v0, v186, s[10:11] offset:1024 sc1
	s_add_u32 s18, s10, 0x2400
	s_addc_u32 s19, s11, 0
	s_waitcnt vmcnt(0)
	v_cmp_eq_u32_e32 vcc, v0, v1
	s_and_saveexec_b64 s[14:15], vcc
	s_cbranch_execz .LBB0_1124
	s_add_u32 s16, s6, 0x4200
	s_addc_u32 s17, s7, 0
	s_mov_b32 s2, 1
	s_mov_b64 s[20:21], 0
	s_branch .LBB0_1115

.LBB0_1124:
	s_or_b64 exec, exec, s[14:15]
.Lb6_join:
	s_waitcnt vmcnt(0)
	s_waitcnt vmcnt(0)
.LBB0_1125:
	s_andn2_saveexec_b64 s[12:13], s[12:13]
	s_cbranch_execz .LBB0_1145
	s_mov_b64 s[12:13], exec
	s_waitcnt lgkmcnt(0)
	s_waitcnt vmcnt(0)
	v_mbcnt_lo_u32_b32 v1, s12, 0
	v_mbcnt_hi_u32_b32 v1, s13, v1
	v_cmp_eq_u32_e32 vcc, 0, v1
	s_and_saveexec_b64 s[14:15], vcc
	s_cbranch_execz .LBB0_1128
	s_bcnt1_i32_b64 s2, s[12:13]
	v_mov_b32_e32 v2, s2
	v_mov_b32_e32 v3, 0x7000
	global_atomic_add v2, v3, v2, s[6:7] offset:1024 sc0

.LBB0_1150:
	v_ashrrev_i32_e32 v1, 31, v8
	v_lshrrev_b32_e32 v1, 26, v1
	v_add_u32_e32 v1, v8, v1
	v_ashrrev_i32_e32 v9, 6, v1
	v_bfe_i32 v1, v8, 27, 1
	v_lshlrev_b32_e32 v0, 4, v8
	v_lshrrev_b32_e32 v1, 22, v1
	v_add_u32_e32 v1, v0, v1
	v_and_b32_e32 v1, 0xfffffc00, v1
	v_sub_u32_e32 v1, v0, v1
	v_lshrrev_b32_e32 v2, 4, v1
	v_bitop3_b32 v2, v2, v1, 32 bitop3:0x6c
	v_ashrrev_i32_e32 v1, 31, v1
	v_lshrrev_b32_e32 v1, 26, v1
	v_add_u32_e32 v1, v2, v1
	s_mul_i32 s7, s70, 0x2800000
	v_ashrrev_i32_e32 v10, 6, v1
	s_waitcnt lgkmcnt(0)
	s_add_u32 s7, s4, s7
	v_lshlrev_b32_e32 v3, 3, v9
	v_mul_i32_i24_e32 v4, 64, v10
	s_addc_u32 s12, s5, 0
	v_and_b32_e32 v3, -16, v3
	v_sub_u32_e32 v2, v2, v4
	s_add_u32 s27, s4, 0x4800000
	v_add_u32_e32 v1, v10, v3
	v_lshlrev_b32_e32 v3, 5, v9
	v_ashrrev_i16_sdwa v2, v189, sext(v2) dst_sel:DWORD dst_unused:UNUSED_PAD src0_sel:DWORD src1_sel:BYTE_0
	s_addc_u32 s30, s5, 0
	v_and_b32_e32 v3, 32, v3
	v_bfe_i32 v11, v2, 0, 16
	s_add_u32 s31, s7, 0xee00000
	v_and_b32_e32 v5, 3, v10
	s_mov_b32 s7, 0x1fffe0
	v_add_lshl_u32 v3, v3, v11, 1
	v_add_u32_e32 v0, 0x2000, v0
	v_lshlrev_b32_e32 v2, 1, v1
	v_lshrrev_b32_e32 v4, 2, v1
	v_and_or_b32 v5, v1, s7, v5
	v_lshl_add_u32 v128, v1, 11, v3
	v_ashrrev_i32_e32 v1, 31, v0
	v_lshrrev_b32_e32 v1, 22, v1
	v_add_u32_e32 v1, v0, v1
	v_ashrrev_i32_e32 v12, 10, v1
	v_mul_i32_i24_e32 v1, 0x400, v12
	v_sub_u32_e32 v0, v0, v1
	v_and_b32_e32 v2, 24, v2
	v_and_b32_e32 v4, 4, v4
	v_lshrrev_b32_e32 v1, 4, v0
	v_or3_b32 v2, v5, v4, v2
	v_bitop3_b32 v0, v1, v0, 32 bitop3:0x6c
	v_lshl_add_u32 v130, v2, 11, v3
	v_ashrrev_i32_e32 v2, 31, v0
	v_lshrrev_b32_e32 v2, 26, v2
	v_lshlrev_b32_e32 v1, 3, v12
	v_add_u32_e32 v2, v0, v2
	v_and_b32_e32 v1, -16, v1
	v_ashrrev_i32_e32 v13, 6, v2
	s_addc_u32 s33, s12, 0
	v_add_u32_e32 v1, v13, v1
	v_and_b32_e32 v4, 3, v13
	s_add_i32 s6, s10, s6
	v_and_or_b32 v4, v1, s7, v4
	s_ashr_i32 s7, s6, 31
	s_lshr_b32 s7, s7, 27
	s_add_i32 s7, s6, s7
	s_ashr_i32 s10, s7, 5
	s_and_b32 s7, s7, 0xffe0
	s_sub_i32 s6, s6, s7
	s_bfe_i32 s7, s6, 0x80000
	s_bfe_u32 s7, s7, 0x3000c
	s_add_i32 s7, s6, s7
	s_lshl_b32 s14, s10, 3
	s_bfe_i32 s10, s7, 0x80000
	s_and_b32 s7, s7, 0xf8
	s_sub_i32 s6, s6, s7
	s_sext_i32_i8 s6, s6
	s_add_i32 s6, s14, s6
	s_ashr_i32 s7, s6, 31
	s_lshr_b32 s7, s7, 27
	s_add_i32 s7, s6, s7
	s_sext_i32_i16 s10, s10
	s_ashr_i32 s24, s7, 5
	s_andn2_b32 s7, s7, 31
	s_lshr_b32 s10, s10, 3
	s_sub_i32 s22, s6, s7
	s_ashr_i32 s13, s11, 6
	s_ashr_i32 s23, s22, 31
	s_ashr_i32 s25, s24, 31
	s_bfe_i64 s[16:17], s[10:11], 0x100000
	s_ashr_i32 s12, s11, 8
	s_lshl_b32 s36, s13, 10
	s_lshl_b64 s[6:7], s[22:23], 19
	s_lshl_b64 s[14:15], s[24:25], 10
	s_lshl_b64 s[16:17], s[16:17], 19
	s_add_u32 s16, s31, s16
	s_addc_u32 s17, s33, s17
	v_and_b32_e32 v2, 0xc0, v2
	s_add_u32 s42, s16, s14
	v_sub_u32_e32 v0, v0, v2
	s_addc_u32 s43, s17, s15
	s_add_i32 s23, s36, 0
	v_ashrrev_i16_sdwa v0, v189, sext(v0) dst_sel:DWORD dst_unused:UNUSED_PAD src0_sel:DWORD src1_sel:BYTE_0
	s_add_i32 m0, s23, 0x10000
	v_lshlrev_b32_e32 v3, 5, v12
	v_bfe_i32 v14, v0, 0, 16
	v_lshlrev_b32_e32 v0, 1, v1
	v_lshrrev_b32_e32 v2, 2, v1
	global_load_lds_dwordx4 v130, s[42:43]
	s_add_i32 m0, s23, 0x12000
	v_and_b32_e32 v3, 32, v3
	v_and_b32_e32 v0, 24, v0
	v_and_b32_e32 v2, 4, v2
	s_add_u32 s16, s27, s6
	v_or3_b32 v0, v4, v2, v0
	v_add_lshl_u32 v2, v3, v14, 1
	s_addc_u32 s17, s30, s7
	v_lshl_add_u32 v134, v0, 11, v2
	s_add_u32 s6, s42, 0x40000
	global_load_lds_dwordx4 v134, s[42:43]
	s_addc_u32 s7, s43, 0
	s_add_i32 m0, s23, 0x14000
	v_lshl_add_u32 v132, v1, 11, v2
	global_load_lds_dwordx4 v130, s[6:7]
	s_add_i32 m0, s23, 0x16000
	s_add_u32 s54, s16, s14
	s_addc_u32 s55, s17, s15
	s_add_i32 s37, s23, 0x2000
	global_load_lds_dwordx4 v134, s[6:7]
	v_cmp_eq_u32_e32 vcc, 0, v147
	s_and_saveexec_b64 s[100:101], vcc
	s_cbranch_execz .Lgw_skip_mo
	v_readlane_b32 s56, v255, 54
	v_readlane_b32 s57, v255, 55
	v_readlane_b32 s58, v255, 50
	v_readlane_b32 s59, v255, 51
	v_readlane_b32 s60, v255, 52
	v_readlane_b32 s61, v255, 53
	s_mov_b32 s62, 0
	s_nop 1
	v_mov_b32_e32 v20, s58
	v_mov_b32_e32 v21, s60
	s_nop 1

.Lgw_skip_mo:
	s_or_b64 exec, exec, s[100:101]
	s_waitcnt vmcnt(4)
	s_barrier
	s_mov_b32 m0, s23
	s_add_u32 s6, s54, 0x40000
	global_load_lds_dwordx4 v128, s[54:55]
	s_mov_b32 m0, s37
	s_addc_u32 s7, s55, 0
	s_add_i32 s40, s23, 0x4000
	global_load_lds_dwordx4 v132, s[54:55]
	s_mov_b32 m0, s40
	s_add_i32 s41, s23, 0x6000
	global_load_lds_dwordx4 v128, s[6:7]
	s_mov_b32 m0, s41
	v_mov_b32_e32 v131, v145
	global_load_lds_dwordx4 v132, s[6:7]
	v_mov_b32_e32 v135, v145
	v_mov_b32_e32 v129, v145
	v_mov_b32_e32 v133, v145
	s_cmp_eq_u32 s12, 1
	v_lshl_add_u64 v[6:7], s[42:43], 0, v[130:131]
	v_lshl_add_u64 v[4:5], s[42:43], 0, v[134:135]
	v_lshl_add_u64 v[0:1], s[54:55], 0, v[128:129]
	s_cselect_b64 s[6:7], -1, 0
	s_cmp_lg_u32 s12, 1
	v_lshl_add_u64 v[2:3], s[54:55], 0, v[132:133]
	s_cbranch_scc1 .LBB0_1152
	s_barrier
